# MLA context-item epilogue: same gate-chunk prefetch as the latent epilogue (v150-179)
# speedup vs baseline: 1.0145x; 1.0145x over previous
.LBB0_527:
	s_or_b64 exec, exec, s[8:9]
	s_nop 0
	v_rcp_f32_e32 v67, v96
	s_lshl_b64 s[6:7], s[6:7], 12
	s_add_u32 s6, s23, s6
	s_addc_u32 s7, s24, s7
	v_mul_f32_e32 v0, v67, v0
	v_mul_f32_e32 v1, v67, v1
	v_cvt_pk_bf16_f32 v80, v0, v1
	v_mul_f32_e32 v0, v67, v2
	v_mul_f32_e32 v1, v67, v3
	v_cvt_pk_bf16_f32 v81, v0, v1
	v_mul_f32_e32 v0, v67, v4
	v_mul_f32_e32 v1, v67, v5
	v_cvt_pk_bf16_f32 v82, v0, v1
	v_mul_f32_e32 v0, v67, v6
	v_mul_f32_e32 v1, v67, v7
	v_cvt_pk_bf16_f32 v83, v0, v1
	v_mul_f32_e32 v0, v67, v8
	v_mul_f32_e32 v1, v67, v9
	v_cvt_pk_bf16_f32 v84, v0, v1
	v_mul_f32_e32 v0, v67, v10
	v_mul_f32_e32 v1, v67, v11
	v_cvt_pk_bf16_f32 v85, v0, v1
	v_mul_f32_e32 v0, v67, v12
	v_mul_f32_e32 v1, v67, v13
	v_cvt_pk_bf16_f32 v86, v0, v1
	v_mul_f32_e32 v0, v67, v14
	v_mul_f32_e32 v1, v67, v15
	v_cvt_pk_bf16_f32 v87, v0, v1
	v_mul_f32_e32 v0, v67, v16
	v_mul_f32_e32 v1, v67, v17
	v_cvt_pk_bf16_f32 v88, v0, v1
	v_mul_f32_e32 v0, v67, v18
	v_mul_f32_e32 v1, v67, v19
	v_cvt_pk_bf16_f32 v89, v0, v1
	v_mul_f32_e32 v0, v67, v20
	v_mul_f32_e32 v1, v67, v21
	v_cvt_pk_bf16_f32 v90, v0, v1
	v_mul_f32_e32 v0, v67, v22
	v_mul_f32_e32 v1, v67, v23
	v_cvt_pk_bf16_f32 v91, v0, v1
	v_mul_f32_e32 v0, v67, v24
	v_mul_f32_e32 v1, v67, v25
	v_cvt_pk_bf16_f32 v92, v0, v1
	v_mul_f32_e32 v0, v67, v26
	v_mul_f32_e32 v1, v67, v27
	v_cvt_pk_bf16_f32 v93, v0, v1
	v_mul_f32_e32 v0, v67, v28
	v_mul_f32_e32 v1, v67, v29
	v_cvt_pk_bf16_f32 v94, v0, v1
	v_mul_f32_e32 v0, v67, v30
	v_mul_f32_e32 v1, v67, v31
	v_cvt_pk_bf16_f32 v95, v0, v1
	v_mul_f32_e32 v0, v67, v32
	v_mul_f32_e32 v1, v67, v33
	v_cvt_pk_bf16_f32 v76, v0, v1
	v_mul_f32_e32 v0, v67, v34
	v_mul_f32_e32 v1, v67, v35
	v_cvt_pk_bf16_f32 v77, v0, v1
	v_mul_f32_e32 v0, v67, v36
	v_mul_f32_e32 v1, v67, v37
	v_cvt_pk_bf16_f32 v78, v0, v1
	v_mul_f32_e32 v0, v67, v38
	v_mul_f32_e32 v1, v67, v39
	v_cvt_pk_bf16_f32 v79, v0, v1
	v_mul_f32_e32 v0, v67, v40
	v_mul_f32_e32 v1, v67, v41
	v_cvt_pk_bf16_f32 v72, v0, v1
	v_mul_f32_e32 v0, v67, v42
	v_mul_f32_e32 v1, v67, v43
	v_cvt_pk_bf16_f32 v73, v0, v1
	v_mul_f32_e32 v0, v67, v44
	v_mul_f32_e32 v1, v67, v45
	v_cvt_pk_bf16_f32 v74, v0, v1
	v_mul_f32_e32 v0, v67, v46
	v_mul_f32_e32 v1, v67, v47
	v_cvt_pk_bf16_f32 v75, v0, v1
	v_mul_f32_e32 v0, v67, v48
	v_mul_f32_e32 v1, v67, v49
	v_cvt_pk_bf16_f32 v68, v0, v1
	v_mul_f32_e32 v0, v67, v50
	v_mul_f32_e32 v1, v67, v51
	v_cvt_pk_bf16_f32 v69, v0, v1
	v_mul_f32_e32 v0, v67, v52
	v_mul_f32_e32 v1, v67, v53
	v_cvt_pk_bf16_f32 v70, v0, v1
	v_mul_f32_e32 v0, v67, v54
	v_mul_f32_e32 v1, v67, v55
	s_lshl_b32 s8, s0, 8
	v_cvt_pk_bf16_f32 v71, v0, v1
	v_mul_f32_e32 v0, v67, v56
	v_mul_f32_e32 v1, v67, v57
	s_add_u32 s6, s6, s8
	v_cvt_pk_bf16_f32 v64, v0, v1
	v_mul_f32_e32 v0, v67, v58
	v_mul_f32_e32 v1, v67, v59
	s_addc_u32 s7, s7, 0
	v_lshl_add_u64 v[150:151], s[6:7], 0, v[200:201]
	v_lshl_add_u64 v[150:151], v[150:151], 0, v[196:197]
	global_load_dwordx2 v[152:153], v[150:151], off offset:32
	global_load_dwordx2 v[154:155], v[150:151], off offset:48
	global_load_dwordx2 v[156:157], v[150:151], off offset:64
	global_load_dwordx2 v[158:159], v[150:151], off offset:80
	global_load_dwordx2 v[160:161], v[150:151], off offset:96
	global_load_dwordx2 v[162:163], v[150:151], off offset:112
	global_load_dwordx2 v[164:165], v[150:151], off offset:128
	global_load_dwordx2 v[166:167], v[150:151], off offset:144
	global_load_dwordx2 v[168:169], v[150:151], off offset:160
	global_load_dwordx2 v[170:171], v[150:151], off offset:176
	global_load_dwordx2 v[172:173], v[150:151], off offset:192
	global_load_dwordx2 v[174:175], v[150:151], off offset:208
	global_load_dwordx2 v[176:177], v[150:151], off offset:224
	global_load_dwordx2 v[178:179], v[150:151], off offset:240
	global_load_dwordx2 v[150:151], v[150:151], off offset:16
	v_cvt_pk_bf16_f32 v65, v0, v1
	v_mul_f32_e32 v0, v67, v60
	v_mul_f32_e32 v1, v67, v61
	s_lshl_b32 s0, s0, 15
	v_cvt_pk_bf16_f32 v66, v0, v1
	v_mul_f32_e32 v0, v67, v62
	v_mul_f32_e32 v1, v67, v63
	v_lshl_add_u64 v[62:63], v[198:199], 0, s[0:1]
	v_cvt_pk_bf16_f32 v67, v0, v1
	global_load_dwordx2 v[0:1], v[62:63], off
	global_load_dwordx2 v[2:3], v[62:63], off offset:16
	global_load_dwordx2 v[16:17], v[62:63], off offset:32
	global_load_dwordx2 v[18:19], v[62:63], off offset:48
	global_load_dwordx2 v[20:21], v[62:63], off offset:64
	global_load_dwordx2 v[22:23], v[62:63], off offset:80
	global_load_dwordx2 v[24:25], v[62:63], off offset:96
	global_load_dwordx2 v[26:27], v[62:63], off offset:112
	global_load_dwordx2 v[28:29], v[62:63], off offset:128
	global_load_dwordx2 v[30:31], v[62:63], off offset:144
	v_add_co_u32_e32 v48, vcc, s27, v62
	s_add_i32 s20, s20, s60
	s_waitcnt vmcnt(0)
	v_mfma_f32_32x32x16_bf16 v[0:15], v[0:3], v[80:83], 0
	v_addc_co_u32_e32 v49, vcc, 0, v63, vcc
	v_add_co_u32_e32 v138, vcc, s17, v62
	s_cmpk_lt_i32 s20, 0x200
	s_nop 0
	v_addc_co_u32_e32 v139, vcc, 0, v63, vcc
	v_mfma_f32_32x32x16_bf16 v[0:15], v[16:19], v[84:87], v[0:15]
	global_load_dwordx2 v[16:17], v[62:63], off offset:160
	global_load_dwordx2 v[18:19], v[62:63], off offset:176
	v_add_co_u32_e32 v146, vcc, s28, v62
	s_nop 1
	v_addc_co_u32_e32 v147, vcc, 0, v63, vcc
	v_mfma_f32_32x32x16_bf16 v[0:15], v[20:23], v[88:91], v[0:15]
	global_load_dwordx2 v[20:21], v[48:49], off
	global_load_dwordx2 v[22:23], v[48:49], off offset:16
	global_load_dwordx2 v[32:33], v[62:63], off offset:192
	global_load_dwordx2 v[34:35], v[62:63], off offset:208
	global_load_dwordx2 v[36:37], v[62:63], off offset:224
	global_load_dwordx2 v[38:39], v[62:63], off offset:240
	global_load_dwordx2 v[40:41], v[48:49], off offset:32
	global_load_dwordx2 v[42:43], v[48:49], off offset:48
	global_load_dwordx2 v[44:45], v[48:49], off offset:64
	global_load_dwordx2 v[46:47], v[48:49], off offset:80
	v_lshl_add_u64 v[62:63], s[6:7], 0, v[200:201]
	v_lshl_add_u64 v[96:97], v[62:63], 0, v[196:197]
	v_mfma_f32_32x32x16_bf16 v[0:15], v[24:27], v[92:95], v[0:15]
	v_mfma_f32_32x32x16_bf16 v[0:15], v[28:31], v[76:79], v[0:15]
	s_waitcnt vmcnt(0)
	v_mfma_f32_32x32x16_bf16 v[0:15], v[16:19], v[72:75], v[0:15]
	v_mfma_f32_32x32x16_bf16 v[0:15], v[32:35], v[68:71], v[0:15]
	global_load_dwordx2 v[32:33], v[48:49], off offset:96
	global_load_dwordx2 v[34:35], v[48:49], off offset:112
	v_mfma_f32_32x32x16_bf16 v[0:15], v[36:39], v[64:67], v[0:15]
	global_load_dwordx2 v[36:37], v[138:139], off
	global_load_dwordx2 v[38:39], v[138:139], off offset:16
	global_load_dwordx2 v[50:51], v[138:139], off offset:32
	global_load_dwordx2 v[52:53], v[138:139], off offset:48
	global_load_dwordx2 v[54:55], v[138:139], off offset:64
	global_load_dwordx2 v[56:57], v[138:139], off offset:80
	global_load_dwordx2 v[58:59], v[138:139], off offset:96
	global_load_dwordx2 v[60:61], v[138:139], off offset:112
	global_load_dwordx2 v[98:99], v[146:147], off
	global_load_dwordx2 v[100:101], v[146:147], off offset:16
	global_load_dwordx2 v[102:103], v[146:147], off offset:32
	global_load_dwordx2 v[104:105], v[146:147], off offset:48
	global_load_dwordx2 v[106:107], v[146:147], off offset:64
	global_load_dwordx2 v[108:109], v[146:147], off offset:80
	global_load_dwordx2 v[148:149], v[96:97], off
	v_mfma_f32_32x32x16_bf16 v[16:31], v[20:23], v[80:83], 0
	global_load_dwordx2 v[110:111], v[146:147], off offset:96
	global_load_dwordx2 v[112:113], v[146:147], off offset:112
	global_load_dwordx2 v[114:115], v[48:49], off offset:128
	global_load_dwordx2 v[116:117], v[48:49], off offset:144
	global_load_dwordx2 v[118:119], v[48:49], off offset:160
	global_load_dwordx2 v[120:121], v[48:49], off offset:176
	global_load_dwordx2 v[122:123], v[48:49], off offset:192
	global_load_dwordx2 v[124:125], v[48:49], off offset:208
	global_load_dwordx2 v[126:127], v[48:49], off offset:224
	global_load_dwordx2 v[128:129], v[48:49], off offset:240
	global_load_dwordx2 v[130:131], v[138:139], off offset:128
	global_load_dwordx2 v[132:133], v[138:139], off offset:144
	global_load_dwordx2 v[134:135], v[138:139], off offset:160
	global_load_dwordx2 v[136:137], v[138:139], off offset:176
	v_mfma_f32_32x32x16_bf16 v[16:31], v[40:43], v[84:87], v[16:31]
	v_mfma_f32_32x32x16_bf16 v[16:31], v[44:47], v[88:91], v[16:31]
	s_waitcnt vmcnt(0)
	v_mfma_f32_32x32x16_bf16 v[16:31], v[32:35], v[92:95], v[16:31]
	v_mfma_f32_32x32x16_bf16 v[32:47], v[36:39], v[80:83], 0
	v_mfma_f32_32x32x16_bf16 v[32:47], v[50:53], v[84:87], v[32:47]
	v_mfma_f32_32x32x16_bf16 v[32:47], v[54:57], v[88:91], v[32:47]
	v_mfma_f32_32x32x16_bf16 v[32:47], v[58:61], v[92:95], v[32:47]
	v_mfma_f32_32x32x16_bf16 v[48:63], v[98:101], v[80:83], 0
	global_load_dwordx2 v[80:81], v[138:139], off offset:192
	global_load_dwordx2 v[82:83], v[138:139], off offset:208
	global_load_dwordx2 v[98:99], v[138:139], off offset:224
	global_load_dwordx2 v[100:101], v[138:139], off offset:240
	s_nop 0
	global_load_dwordx2 v[138:139], v[146:147], off offset:128
	global_load_dwordx2 v[140:141], v[146:147], off offset:144
	global_load_dwordx2 v[142:143], v[146:147], off offset:160
	global_load_dwordx2 v[144:145], v[146:147], off offset:176
	v_mfma_f32_32x32x16_bf16 v[48:63], v[102:105], v[84:87], v[48:63]
	global_load_dwordx2 v[84:85], v[146:147], off offset:192
	global_load_dwordx2 v[86:87], v[146:147], off offset:208
	global_load_dwordx2 v[102:103], v[146:147], off offset:224
	global_load_dwordx2 v[104:105], v[146:147], off offset:240
	v_lshlrev_b32_e32 v146, 16, v148
	v_and_b32_e32 v147, 0xffff0000, v148
	v_lshlrev_b32_e32 v148, 16, v149
	v_mul_f32_e32 v0, v0, v146
	v_mul_f32_e32 v1, v1, v147
	v_cvt_pk_bf16_f32 v0, v0, v1
	v_mfma_f32_32x32x16_bf16 v[48:63], v[106:109], v[88:91], v[48:63]
	v_and_b32_e32 v88, 0xffff0000, v149
	v_mul_f32_e32 v1, v2, v148
	v_mul_f32_e32 v2, v3, v88
	v_cvt_pk_bf16_f32 v1, v1, v2
	s_nop 0
	global_store_dwordx2 v[96:97], v[0:1], off
	v_mfma_f32_32x32x16_bf16 v[16:31], v[114:117], v[76:79], v[16:31]
	s_waitcnt vmcnt(1)
	v_lshlrev_b32_e32 v0, 16, v150
	v_and_b32_e32 v1, 0xffff0000, v150
	v_lshlrev_b32_e32 v2, 16, v151
	v_and_b32_e32 v3, 0xffff0000, v151
	v_mul_f32_e32 v0, v4, v0
	v_mul_f32_e32 v1, v5, v1
	v_mul_f32_e32 v2, v6, v2
	v_mul_f32_e32 v3, v7, v3
	v_cvt_pk_bf16_f32 v0, v0, v1
	v_cvt_pk_bf16_f32 v1, v2, v3
	v_mfma_f32_32x32x16_bf16 v[16:31], v[118:121], v[72:75], v[16:31]
	global_store_dwordx2 v[96:97], v[0:1], off offset:16
	v_lshlrev_b32_e32 v0, 16, v152
	v_and_b32_e32 v1, 0xffff0000, v152
	v_lshlrev_b32_e32 v2, 16, v153
	v_and_b32_e32 v3, 0xffff0000, v153
	v_mul_f32_e32 v0, v8, v0
	v_mul_f32_e32 v1, v9, v1
	v_mul_f32_e32 v2, v10, v2
	v_mul_f32_e32 v3, v11, v3
	v_cvt_pk_bf16_f32 v0, v0, v1
	v_cvt_pk_bf16_f32 v1, v2, v3
	v_mfma_f32_32x32x16_bf16 v[16:31], v[122:125], v[68:71], v[16:31]
	global_store_dwordx2 v[96:97], v[0:1], off offset:32
	v_lshlrev_b32_e32 v0, 16, v154
	v_and_b32_e32 v1, 0xffff0000, v154
	v_lshlrev_b32_e32 v2, 16, v155
	v_and_b32_e32 v3, 0xffff0000, v155
	v_mul_f32_e32 v0, v12, v0
	v_mul_f32_e32 v1, v13, v1
	v_mul_f32_e32 v2, v14, v2
	v_mul_f32_e32 v3, v15, v3
	v_cvt_pk_bf16_f32 v0, v0, v1
	v_cvt_pk_bf16_f32 v1, v2, v3
	v_mfma_f32_32x32x16_bf16 v[16:31], v[126:129], v[64:67], v[16:31]
	global_store_dwordx2 v[96:97], v[0:1], off offset:48
	v_lshlrev_b32_e32 v0, 16, v156
	v_and_b32_e32 v1, 0xffff0000, v156
	v_lshlrev_b32_e32 v2, 16, v157
	v_and_b32_e32 v3, 0xffff0000, v157
	s_nop 5
	v_mul_f32_e32 v0, v16, v0
	v_mul_f32_e32 v1, v17, v1
	v_mul_f32_e32 v2, v18, v2
	v_mul_f32_e32 v3, v19, v3
	v_cvt_pk_bf16_f32 v0, v0, v1
	v_cvt_pk_bf16_f32 v1, v2, v3
	v_mfma_f32_32x32x16_bf16 v[32:47], v[130:133], v[76:79], v[32:47]
	global_store_dwordx2 v[96:97], v[0:1], off offset:64
	v_lshlrev_b32_e32 v0, 16, v158
	v_and_b32_e32 v1, 0xffff0000, v158
	v_lshlrev_b32_e32 v2, 16, v159
	v_and_b32_e32 v3, 0xffff0000, v159
	v_mul_f32_e32 v0, v20, v0
	v_mul_f32_e32 v1, v21, v1
	v_mul_f32_e32 v2, v22, v2
	v_mul_f32_e32 v3, v23, v3
	v_cvt_pk_bf16_f32 v0, v0, v1
	v_cvt_pk_bf16_f32 v1, v2, v3
	v_mfma_f32_32x32x16_bf16 v[32:47], v[134:137], v[72:75], v[32:47]
	global_store_dwordx2 v[96:97], v[0:1], off offset:80
	v_lshlrev_b32_e32 v0, 16, v160
	v_and_b32_e32 v1, 0xffff0000, v160
	v_lshlrev_b32_e32 v2, 16, v161
	v_and_b32_e32 v3, 0xffff0000, v161
	v_mul_f32_e32 v0, v24, v0
	v_mul_f32_e32 v1, v25, v1
	v_mul_f32_e32 v2, v26, v2
	v_mul_f32_e32 v3, v27, v3
	v_cvt_pk_bf16_f32 v0, v0, v1
	v_cvt_pk_bf16_f32 v1, v2, v3
	v_mfma_f32_32x32x16_bf16 v[32:47], v[80:83], v[68:71], v[32:47]
	global_store_dwordx2 v[96:97], v[0:1], off offset:96
	v_lshlrev_b32_e32 v0, 16, v162
	v_and_b32_e32 v1, 0xffff0000, v162
	v_lshlrev_b32_e32 v2, 16, v163
	v_and_b32_e32 v3, 0xffff0000, v163
	v_mul_f32_e32 v0, v28, v0
	v_mul_f32_e32 v1, v29, v1
	v_mul_f32_e32 v2, v30, v2
	v_mul_f32_e32 v3, v31, v3
	v_cvt_pk_bf16_f32 v0, v0, v1
	v_cvt_pk_bf16_f32 v1, v2, v3
	v_mfma_f32_32x32x16_bf16 v[32:47], v[98:101], v[64:67], v[32:47]
	global_store_dwordx2 v[96:97], v[0:1], off offset:112
	v_lshlrev_b32_e32 v0, 16, v164
	v_and_b32_e32 v1, 0xffff0000, v164
	v_lshlrev_b32_e32 v2, 16, v165
	v_and_b32_e32 v3, 0xffff0000, v165
	s_nop 5
	v_mul_f32_e32 v0, v32, v0
	v_mul_f32_e32 v1, v33, v1
	v_mul_f32_e32 v2, v34, v2
	v_mul_f32_e32 v3, v35, v3
	v_cvt_pk_bf16_f32 v0, v0, v1
	v_cvt_pk_bf16_f32 v1, v2, v3
	v_mfma_f32_32x32x16_bf16 v[48:63], v[110:113], v[92:95], v[48:63]
	global_store_dwordx2 v[96:97], v[0:1], off offset:128
	v_lshlrev_b32_e32 v0, 16, v166
	v_and_b32_e32 v1, 0xffff0000, v166
	v_lshlrev_b32_e32 v2, 16, v167
	v_and_b32_e32 v3, 0xffff0000, v167
	v_mul_f32_e32 v0, v36, v0
	v_mul_f32_e32 v1, v37, v1
	v_mul_f32_e32 v2, v38, v2
	v_mul_f32_e32 v3, v39, v3
	v_cvt_pk_bf16_f32 v0, v0, v1
	v_cvt_pk_bf16_f32 v1, v2, v3
	v_mfma_f32_32x32x16_bf16 v[48:63], v[138:141], v[76:79], v[48:63]
	global_store_dwordx2 v[96:97], v[0:1], off offset:144
	v_lshlrev_b32_e32 v0, 16, v168
	v_and_b32_e32 v1, 0xffff0000, v168
	v_lshlrev_b32_e32 v2, 16, v169
	v_and_b32_e32 v3, 0xffff0000, v169
	v_mul_f32_e32 v0, v40, v0
	v_mul_f32_e32 v1, v41, v1
	v_mul_f32_e32 v2, v42, v2
	v_mul_f32_e32 v3, v43, v3
	v_cvt_pk_bf16_f32 v0, v0, v1
	v_cvt_pk_bf16_f32 v1, v2, v3
	v_mfma_f32_32x32x16_bf16 v[48:63], v[142:145], v[72:75], v[48:63]
	global_store_dwordx2 v[96:97], v[0:1], off offset:160
	v_lshlrev_b32_e32 v0, 16, v170
	v_and_b32_e32 v1, 0xffff0000, v170
	v_lshlrev_b32_e32 v2, 16, v171
	v_and_b32_e32 v3, 0xffff0000, v171
	v_mul_f32_e32 v0, v44, v0
	v_mul_f32_e32 v1, v45, v1
	v_mul_f32_e32 v2, v46, v2
	v_mul_f32_e32 v3, v47, v3
	v_cvt_pk_bf16_f32 v0, v0, v1
	v_cvt_pk_bf16_f32 v1, v2, v3
	v_mfma_f32_32x32x16_bf16 v[48:63], v[84:87], v[68:71], v[48:63]
	global_store_dwordx2 v[96:97], v[0:1], off offset:176
	v_lshlrev_b32_e32 v0, 16, v172
	v_mfma_f32_32x32x16_bf16 v[48:63], v[102:105], v[64:67], v[48:63]
	v_and_b32_e32 v1, 0xffff0000, v172
	v_lshlrev_b32_e32 v2, 16, v173
	v_and_b32_e32 v3, 0xffff0000, v173
	s_nop 8
	v_mul_f32_e32 v0, v48, v0
	v_mul_f32_e32 v1, v49, v1
	v_mul_f32_e32 v2, v50, v2
	v_mul_f32_e32 v3, v51, v3
	v_cvt_pk_bf16_f32 v0, v0, v1
	v_cvt_pk_bf16_f32 v1, v2, v3
	s_nop 0
	global_store_dwordx2 v[96:97], v[0:1], off offset:192
	v_lshlrev_b32_e32 v0, 16, v174
	v_and_b32_e32 v1, 0xffff0000, v174
	v_lshlrev_b32_e32 v2, 16, v175
	v_and_b32_e32 v3, 0xffff0000, v175
	v_mul_f32_e32 v0, v52, v0
	v_mul_f32_e32 v1, v53, v1
	v_mul_f32_e32 v2, v54, v2
	v_mul_f32_e32 v3, v55, v3
	v_cvt_pk_bf16_f32 v0, v0, v1
	v_cvt_pk_bf16_f32 v1, v2, v3
	s_nop 0
	global_store_dwordx2 v[96:97], v[0:1], off offset:208
	v_lshlrev_b32_e32 v0, 16, v176
	v_and_b32_e32 v1, 0xffff0000, v176
	v_lshlrev_b32_e32 v2, 16, v177
	v_and_b32_e32 v3, 0xffff0000, v177
	v_mul_f32_e32 v0, v56, v0
	v_mul_f32_e32 v1, v57, v1
	v_mul_f32_e32 v2, v58, v2
	v_mul_f32_e32 v3, v59, v3
	v_cvt_pk_bf16_f32 v0, v0, v1
	v_cvt_pk_bf16_f32 v1, v2, v3
	s_nop 0
	global_store_dwordx2 v[96:97], v[0:1], off offset:224
	v_lshlrev_b32_e32 v0, 16, v178
	v_and_b32_e32 v1, 0xffff0000, v178
	v_lshlrev_b32_e32 v2, 16, v179
	v_and_b32_e32 v3, 0xffff0000, v179
	v_mul_f32_e32 v0, v60, v0
	v_mul_f32_e32 v1, v61, v1
	v_mul_f32_e32 v2, v62, v2
	v_mul_f32_e32 v3, v63, v3
	v_cvt_pk_bf16_f32 v0, v0, v1
	v_cvt_pk_bf16_f32 v1, v2, v3
	global_store_dwordx2 v[96:97], v[0:1], off offset:240
	s_waitcnt lgkmcnt(0)
	s_barrier
	s_cbranch_scc0 .LBB0_548
